# attention: two-barrier ping-pong between wave groups (X = staging+QK+softmax g0 | Y = softmax g1+PV), K/V triple-buffered
# speedup vs baseline: 1.0047x; 1.0035x over previous
.LBB0_113:
	v_mbcnt_lo_u32_b32 v209, -1, 0
	v_mbcnt_hi_u32_b32 v209, -1, v209
	v_readlane_b32 s98, v254, 54
	s_nop 3
	v_lshl_add_u32 v209, s98, 6, v209
	v_lshlrev_b32_e32 v209, 2, v209
	v_add_u32_e32 v209, 0x10000, v209
	ds_write_b32 v209, v184 offset:0
	ds_write_b32 v209, v187 offset:2048
	ds_write_b32 v209, v188 offset:4096
	ds_write_b32 v209, v189 offset:6144
	ds_write_b32 v209, v190 offset:8192
	ds_write_b32 v209, v191 offset:10240
	ds_write_b32 v209, v192 offset:12288
	ds_write_b32 v209, v193 offset:14336
	ds_write_b32 v209, v194 offset:16384
	ds_write_b32 v209, v195 offset:18432
	ds_write_b32 v209, v196 offset:20480
	ds_write_b32 v209, v198 offset:22528
	ds_write_b32 v209, v200 offset:24576
	ds_write_b32 v209, v201 offset:26624
	ds_write_b32 v209, v202 offset:28672
	ds_write_b32 v209, v203 offset:30720
	s_cmp_lt_i32 s11, -3
	s_waitcnt lgkmcnt(0)
	s_barrier
	s_cbranch_scc1 .LBB0_90
	v_lshl_add_u64 v[8:9], s[2:3], 0, v[190:191]
	v_lshl_add_u64 v[204:205], v[8:9], 0, v[0:1]
	v_lshl_add_u64 v[206:207], v[6:7], 0, v[0:1]
	v_add_u32_e32 v0, s28, v220
	v_mov_b32_e32 v14, v1
	v_mov_b32_e32 v15, v1
	v_cndmask_b32_e64 v228, v196, v4, s[38:39]
	v_cndmask_b32_e64 v229, v194, v2, s[38:39]
	v_add_u32_e32 v230, 0xffffff80, v0
	v_add_u32_e32 v231, 0xbf, v0
	v_mov_b32_e32 v0, v1
	v_mov_b32_e32 v2, v1
	v_mov_b32_e32 v3, v1
	v_mov_b32_e32 v4, v1
	v_mov_b32_e32 v5, v1
	v_mov_b32_e32 v6, v1
	v_mov_b32_e32 v7, v1
	v_mov_b32_e32 v8, v1
	v_mov_b32_e32 v9, v1
	v_mov_b32_e32 v10, v1
	v_mov_b32_e32 v11, v1
	v_mov_b32_e32 v12, v1
	v_mov_b32_e32 v13, v1
	v_mov_b64_e32 v[78:79], v[14:15]
	v_mov_b64_e32 v[62:63], v[14:15]
	v_mov_b64_e32 v[46:47], v[14:15]
	v_mov_b64_e32 v[30:31], v[14:15]
	s_add_i32 s18, s11, 4
	s_sub_i32 s19, s10, s8
	s_mov_b32 s49, 0
	v_mov_b64_e32 v[76:77], v[12:13]
	v_mov_b64_e32 v[74:75], v[10:11]
	v_mov_b64_e32 v[72:73], v[8:9]
	v_mov_b64_e32 v[70:71], v[6:7]
	v_mov_b64_e32 v[68:69], v[4:5]
	v_mov_b64_e32 v[66:67], v[2:3]
	v_mov_b64_e32 v[64:65], v[0:1]
	v_mov_b64_e32 v[60:61], v[12:13]
	v_mov_b64_e32 v[58:59], v[10:11]
	v_mov_b64_e32 v[56:57], v[8:9]
	v_mov_b64_e32 v[54:55], v[6:7]
	v_mov_b64_e32 v[52:53], v[4:5]
	v_mov_b64_e32 v[50:51], v[2:3]
	v_mov_b64_e32 v[48:49], v[0:1]
	v_mov_b64_e32 v[44:45], v[12:13]
	v_mov_b64_e32 v[42:43], v[10:11]
	v_mov_b64_e32 v[40:41], v[8:9]
	v_mov_b64_e32 v[38:39], v[6:7]
	v_mov_b64_e32 v[36:37], v[4:5]
	v_mov_b64_e32 v[34:35], v[2:3]
	v_mov_b64_e32 v[32:33], v[0:1]
	v_mov_b64_e32 v[28:29], v[12:13]
	v_mov_b64_e32 v[26:27], v[10:11]
	v_mov_b64_e32 v[24:25], v[8:9]
	v_mov_b64_e32 v[22:23], v[6:7]
	v_mov_b64_e32 v[20:21], v[4:5]
	v_mov_b64_e32 v[18:19], v[2:3]
	v_mov_b64_e32 v[16:17], v[0:1]
	s_mov_b32 s84, 0x8000
	v_readlane_b32 s85, v255, 4
	v_readlane_b32 s94, v255, 5
	v_mov_b32_e32 v187, 0xf0c9f2ca
	v_cmp_lt_f32_e32 vcc, v226, v187
	s_nop 1
	v_cndmask_b32_e64 v184, v226, 0, vcc
	v_sub_f32_e32 v188, 0, v184
	v_sub_f32_e32 v189, 0, v184
	v_sub_f32_e32 v190, 0, v184
	v_sub_f32_e32 v191, 0, v184
	v_sub_f32_e32 v192, 0, v184
	v_sub_f32_e32 v193, 0, v184
	v_sub_f32_e32 v194, 0, v184
	v_sub_f32_e32 v195, 0, v184
	v_sub_f32_e32 v196, 0, v184
	v_sub_f32_e32 v197, 0, v184
	v_sub_f32_e32 v198, 0, v184
	v_sub_f32_e32 v199, 0, v184
	v_sub_f32_e32 v200, 0, v184
	v_sub_f32_e32 v201, 0, v184
	v_sub_f32_e32 v202, 0, v184
	v_sub_f32_e32 v203, 0, v184
	s_mov_b32 s100, 0
	s_movk_i32 s101, 0x4800
	v_readlane_b32 s98, v254, 54
	s_nop 3
	s_cmp_lt_u32 s98, 4
	s_cbranch_scc1 .Lattn_g0
	s_barrier
.Lattn_g0:
.LBB0_115:
	s_add_i32 s25, s49, 1
	s_cmp_ge_i32 s25, s18
	s_cselect_b64 s[28:29], -1, 0
	s_and_b64 vcc, exec, s[28:29]
	s_cbranch_vccnz .LBB0_117
	s_mov_b32 s2, s101
	s_nop 0
	v_add_u32_e32 v0, s2, v219
	s_waitcnt vmcnt(1)
	ds_write_b128 v0, v[176:179]
	s_waitcnt vmcnt(0)
	ds_write_b128 v0, v[180:183] offset:9216

.LBB0_121:
	s_and_saveexec_b64 s[44:45], s[8:9]
	s_cbranch_execz .Lattn_skipx
	s_mov_b32 s8, s100
	s_nop 0
	s_add_i32 s8, s8, 16
	v_add3_u32 v0, s8, v186, v224
	ds_read_b128 v[2:5], v0
	s_and_b64 s[2:3], s[16:17], s[2:3]
	v_add_u32_e32 v6, 64, v230
	v_cmp_ge_i32_e64 s[98:99], s48, v6
	v_add_u32_e32 v6, 0xffffff81, v231
	v_cmp_le_i32_e64 vcc, s48, v6
	s_nop 1
	s_and_b64 s[98:99], s[98:99], vcc
	s_andn2_b64 s[2:3], s[2:3], s[98:99]
	v_cndmask_b32_e64 v6, 0, 1, s[2:3]
	v_cmp_ne_u32_e64 s[38:39], 1, v6
	s_andn2_b64 vcc, exec, s[2:3]
	ds_read_b128 v[6:9], v0 offset:32
	ds_read_b128 v[10:13], v0 offset:64
	s_waitcnt lgkmcnt(2)
	v_mfma_f32_32x32x16_bf16 v[112:127], v[2:5], v[144:147], v[234:249]
	v_mfma_f32_32x32x16_bf16 v[96:111], v[2:5], v[160:163], v[188:203]
	ds_read_b128 v[2:5], v0 offset:96
	s_waitcnt lgkmcnt(2)
	v_mfma_f32_32x32x16_bf16 v[112:127], v[6:9], v[148:151], v[112:127]
	v_mfma_f32_32x32x16_bf16 v[96:111], v[6:9], v[164:167], v[96:111]
	ds_read_b128 v[6:9], v0 offset:4608
	s_waitcnt lgkmcnt(2)
	v_mfma_f32_32x32x16_bf16 v[112:127], v[10:13], v[152:155], v[112:127]
	v_mfma_f32_32x32x16_bf16 v[96:111], v[10:13], v[168:171], v[96:111]
	ds_read_b128 v[10:13], v0 offset:4640
	s_waitcnt lgkmcnt(2)
	v_mfma_f32_32x32x16_bf16 v[112:127], v[2:5], v[156:159], v[112:127]
	v_mfma_f32_32x32x16_bf16 v[96:111], v[2:5], v[172:175], v[96:111]
	ds_read_b128 v[2:5], v0 offset:4672
	s_waitcnt lgkmcnt(2)
	v_mfma_f32_32x32x16_bf16 v[128:143], v[6:9], v[144:147], v[234:249]
	v_mfma_f32_32x32x16_bf16 v[80:95], v[6:9], v[160:163], v[188:203]
	ds_read_b128 v[6:9], v0 offset:4704
	v_add_u32_e32 v0, s48, v221
	s_waitcnt lgkmcnt(2)
	v_mfma_f32_32x32x16_bf16 v[128:143], v[10:13], v[148:151], v[128:143]
	v_mfma_f32_32x32x16_bf16 v[80:95], v[10:13], v[164:167], v[80:95]
	s_waitcnt lgkmcnt(1)
	v_mfma_f32_32x32x16_bf16 v[128:143], v[2:5], v[152:155], v[128:143]
	v_mfma_f32_32x32x16_bf16 v[80:95], v[2:5], v[168:171], v[80:95]
	s_waitcnt lgkmcnt(0)
	v_mfma_f32_32x32x16_bf16 v[128:143], v[6:9], v[156:159], v[128:143]
	v_mfma_f32_32x32x16_bf16 v[80:95], v[6:9], v[172:175], v[80:95]
	s_cbranch_vccnz .LBB0_124
	v_sub_u32_e32 v2, v0, v229
	s_movk_i32 s0, 0xfefe
	v_cmp_lt_u32_e32 vcc, s0, v2
	v_add_u32_e32 v3, 1, v2
	s_nop 0
	v_cndmask_b32_e32 v112, v210, v112, vcc
	v_cmp_lt_u32_e32 vcc, s0, v3
	v_add_u32_e32 v3, 2, v2
	s_nop 0
	v_cndmask_b32_e32 v113, v210, v113, vcc
	v_cmp_lt_u32_e32 vcc, s0, v3
	v_add_u32_e32 v3, 3, v2
	s_nop 0
	v_cndmask_b32_e32 v114, v210, v114, vcc
	v_cmp_lt_u32_e32 vcc, s0, v3
	v_add_u32_e32 v3, 8, v2
	s_nop 0
	v_cndmask_b32_e32 v115, v210, v115, vcc
	v_cmp_lt_u32_e32 vcc, s0, v3
	v_add_u32_e32 v3, 9, v2
	s_nop 0
	v_cndmask_b32_e32 v116, v210, v116, vcc
	v_cmp_lt_u32_e32 vcc, s0, v3
	v_add_u32_e32 v3, 10, v2
	s_nop 0
	v_cndmask_b32_e32 v117, v210, v117, vcc
	v_cmp_lt_u32_e32 vcc, s0, v3
	v_add_u32_e32 v3, 11, v2
	s_nop 0
	v_cndmask_b32_e32 v118, v210, v118, vcc
	v_cmp_lt_u32_e32 vcc, s0, v3
	v_add_u32_e32 v3, 16, v2
	s_nop 0
	v_cndmask_b32_e32 v119, v210, v119, vcc
	v_cmp_lt_u32_e32 vcc, s0, v3
	v_add_u32_e32 v3, 17, v2
	s_nop 0
	v_cndmask_b32_e32 v120, v210, v120, vcc
	v_cmp_lt_u32_e32 vcc, s0, v3
	v_add_u32_e32 v3, 18, v2
	s_nop 0
	v_cndmask_b32_e32 v121, v210, v121, vcc
	v_cmp_lt_u32_e32 vcc, s0, v3
	v_add_u32_e32 v3, 19, v2
	s_nop 0
	v_cndmask_b32_e32 v122, v210, v122, vcc
	v_cmp_lt_u32_e32 vcc, s0, v3
	v_add_u32_e32 v3, 24, v2
	s_nop 0
	v_cndmask_b32_e32 v123, v210, v123, vcc
	v_cmp_lt_u32_e32 vcc, s0, v3
	v_add_u32_e32 v3, 25, v2
	s_nop 0
	v_cndmask_b32_e32 v124, v210, v124, vcc
	v_cmp_lt_u32_e32 vcc, s0, v3
	v_add_u32_e32 v3, 26, v2
	s_nop 0
	v_cndmask_b32_e32 v125, v210, v125, vcc
	v_cmp_lt_u32_e32 vcc, s0, v3
	v_add_u32_e32 v3, 27, v2
	s_nop 0
	v_cndmask_b32_e32 v126, v210, v126, vcc
	v_cmp_lt_u32_e32 vcc, s0, v3
	v_add_u32_e32 v3, 32, v2
	s_nop 0
	v_cndmask_b32_e32 v127, v210, v127, vcc
	v_cmp_lt_u32_e32 vcc, s0, v3
	v_add_u32_e32 v3, 33, v2
	s_nop 0
	v_cndmask_b32_e32 v128, v210, v128, vcc
	v_cmp_lt_u32_e32 vcc, s0, v3
	v_add_u32_e32 v3, 34, v2
	s_nop 0
	v_cndmask_b32_e32 v129, v210, v129, vcc
	v_cmp_lt_u32_e32 vcc, s0, v3
	v_add_u32_e32 v3, 35, v2
	s_nop 0
	v_cndmask_b32_e32 v130, v210, v130, vcc
	v_cmp_lt_u32_e32 vcc, s0, v3
	v_add_u32_e32 v3, 40, v2
	s_nop 0
	v_cndmask_b32_e32 v131, v210, v131, vcc
	v_cmp_lt_u32_e32 vcc, s0, v3
	v_add_u32_e32 v3, 41, v2
	s_nop 0
	v_cndmask_b32_e32 v132, v210, v132, vcc
	v_cmp_lt_u32_e32 vcc, s0, v3
	v_add_u32_e32 v3, 42, v2
	s_nop 0
	v_cndmask_b32_e32 v133, v210, v133, vcc
	v_cmp_lt_u32_e32 vcc, s0, v3
	v_add_u32_e32 v3, 43, v2
	s_nop 0
	v_cndmask_b32_e32 v134, v210, v134, vcc
	v_cmp_lt_u32_e32 vcc, s0, v3
	v_add_u32_e32 v3, 48, v2
	s_nop 0
	v_cndmask_b32_e32 v135, v210, v135, vcc
	v_cmp_lt_u32_e32 vcc, s0, v3
	v_add_u32_e32 v3, 49, v2
	s_nop 0
	v_cndmask_b32_e32 v136, v210, v136, vcc
	v_cmp_lt_u32_e32 vcc, s0, v3
	v_add_u32_e32 v3, 50, v2
	s_nop 0
	v_cndmask_b32_e32 v137, v210, v137, vcc
	v_cmp_lt_u32_e32 vcc, s0, v3
	v_add_u32_e32 v3, 51, v2
	s_nop 0
	v_cndmask_b32_e32 v138, v210, v138, vcc
	v_cmp_lt_u32_e32 vcc, s0, v3
	v_add_u32_e32 v3, 56, v2
	s_nop 0
	v_cndmask_b32_e32 v139, v210, v139, vcc
	v_cmp_lt_u32_e32 vcc, s0, v3
	v_add_u32_e32 v3, 57, v2
	s_nop 0
	v_cndmask_b32_e32 v140, v210, v140, vcc
	v_cmp_lt_u32_e32 vcc, s0, v3
	v_add_u32_e32 v3, 58, v2
	v_add_u32_e32 v2, 59, v2
	v_cndmask_b32_e32 v141, v210, v141, vcc
	v_cmp_lt_u32_e32 vcc, s0, v3
	s_nop 1
	v_cndmask_b32_e32 v142, v210, v142, vcc
	v_cmp_lt_u32_e32 vcc, s0, v2
	s_nop 1
	v_cndmask_b32_e32 v143, v210, v143, vcc

.LBB0_126:
	v_exp_f32_e32 v14, v112
	v_exp_f32_e32 v15, v113
	v_exp_f32_e32 v232, v114
	v_exp_f32_e32 v233, v115
	v_exp_f32_e32 v116, v116
	v_exp_f32_e32 v117, v117
	v_exp_f32_e32 v118, v118
	v_exp_f32_e32 v119, v119
	v_exp_f32_e32 v120, v120
	v_exp_f32_e32 v121, v121
	v_exp_f32_e32 v122, v122
	v_exp_f32_e32 v123, v123
	v_exp_f32_e32 v124, v124
	v_exp_f32_e32 v125, v125
	v_exp_f32_e32 v126, v126
	v_exp_f32_e32 v127, v127
	v_exp_f32_e32 v128, v128
	v_exp_f32_e32 v129, v129
	v_exp_f32_e32 v130, v130
	v_exp_f32_e32 v131, v131
	v_exp_f32_e32 v132, v132
	v_exp_f32_e32 v133, v133
	v_exp_f32_e32 v134, v134
	v_exp_f32_e32 v135, v135
	v_exp_f32_e32 v136, v136
	v_exp_f32_e32 v137, v137
	v_exp_f32_e32 v138, v138
	v_exp_f32_e32 v139, v139
	v_exp_f32_e32 v140, v140
	v_exp_f32_e32 v141, v141
	v_exp_f32_e32 v142, v142
	v_exp_f32_e32 v143, v143
	s_and_b64 vcc, exec, s[38:39]
	v_cvt_pk_bf16_f32 v112, v14, v15
	v_cvt_pk_bf16_f32 v113, v232, v233
	v_cvt_pk_bf16_f32 v114, v116, v117
	v_cvt_pk_bf16_f32 v115, v118, v119
	v_cvt_pk_bf16_f32 v10, v120, v121
	v_cvt_pk_bf16_f32 v11, v122, v123
	v_cvt_pk_bf16_f32 v12, v124, v125
	v_cvt_pk_bf16_f32 v13, v126, v127
	v_cvt_pk_bf16_f32 v6, v128, v129
	v_cvt_pk_bf16_f32 v7, v130, v131
	v_cvt_pk_bf16_f32 v8, v132, v133
	v_cvt_pk_bf16_f32 v9, v134, v135
	v_cvt_pk_bf16_f32 v2, v136, v137
	v_cvt_pk_bf16_f32 v3, v138, v139
	v_cvt_pk_bf16_f32 v4, v140, v141
	v_cvt_pk_bf16_f32 v5, v142, v143
	s_waitcnt lgkmcnt(0)
	s_barrier
	s_cbranch_vccnz .LBB0_128
	v_sub_u32_e32 v0, v0, v228
	s_movk_i32 s0, 0xfefe
	v_cmp_lt_u32_e32 vcc, s0, v0
	v_add_u32_e32 v214, 1, v0
	s_nop 0
	v_cndmask_b32_e32 v96, v210, v96, vcc
	v_cmp_lt_u32_e32 vcc, s0, v214
	v_add_u32_e32 v214, 2, v0
	s_nop 0
	v_cndmask_b32_e32 v97, v210, v97, vcc
	v_cmp_lt_u32_e32 vcc, s0, v214
	v_add_u32_e32 v214, 3, v0
	s_nop 0
	v_cndmask_b32_e32 v98, v210, v98, vcc
	v_cmp_lt_u32_e32 vcc, s0, v214
	v_add_u32_e32 v214, 8, v0
	s_nop 0
	v_cndmask_b32_e32 v99, v210, v99, vcc
	v_cmp_lt_u32_e32 vcc, s0, v214
	v_add_u32_e32 v214, 9, v0
	s_nop 0
	v_cndmask_b32_e32 v100, v210, v100, vcc
	v_cmp_lt_u32_e32 vcc, s0, v214
	v_add_u32_e32 v214, 10, v0
	s_nop 0
	v_cndmask_b32_e32 v101, v210, v101, vcc
	v_cmp_lt_u32_e32 vcc, s0, v214
	v_add_u32_e32 v214, 11, v0
	s_nop 0
	v_cndmask_b32_e32 v102, v210, v102, vcc
	v_cmp_lt_u32_e32 vcc, s0, v214
	v_add_u32_e32 v214, 16, v0
	s_nop 0
	v_cndmask_b32_e32 v103, v210, v103, vcc
	v_cmp_lt_u32_e32 vcc, s0, v214
	v_add_u32_e32 v214, 17, v0
	s_nop 0
	v_cndmask_b32_e32 v104, v210, v104, vcc
	v_cmp_lt_u32_e32 vcc, s0, v214
	v_add_u32_e32 v214, 18, v0
	s_nop 0
	v_cndmask_b32_e32 v105, v210, v105, vcc
	v_cmp_lt_u32_e32 vcc, s0, v214
	v_add_u32_e32 v214, 19, v0
	s_nop 0
	v_cndmask_b32_e32 v106, v210, v106, vcc
	v_cmp_lt_u32_e32 vcc, s0, v214
	v_add_u32_e32 v214, 24, v0
	s_nop 0
	v_cndmask_b32_e32 v107, v210, v107, vcc
	v_cmp_lt_u32_e32 vcc, s0, v214
	v_add_u32_e32 v214, 25, v0
	s_nop 0
	v_cndmask_b32_e32 v108, v210, v108, vcc
	v_cmp_lt_u32_e32 vcc, s0, v214
	v_add_u32_e32 v214, 26, v0
	s_nop 0
	v_cndmask_b32_e32 v109, v210, v109, vcc
	v_cmp_lt_u32_e32 vcc, s0, v214
	v_add_u32_e32 v214, 27, v0
	s_nop 0
	v_cndmask_b32_e32 v110, v210, v110, vcc
	v_cmp_lt_u32_e32 vcc, s0, v214
	v_add_u32_e32 v214, 32, v0
	s_nop 0
	v_cndmask_b32_e32 v111, v210, v111, vcc
	v_cmp_lt_u32_e32 vcc, s0, v214
	v_add_u32_e32 v214, 33, v0
	s_nop 0
	v_cndmask_b32_e32 v80, v210, v80, vcc
	v_cmp_lt_u32_e32 vcc, s0, v214
	v_add_u32_e32 v214, 34, v0
	s_nop 0
	v_cndmask_b32_e32 v81, v210, v81, vcc
	v_cmp_lt_u32_e32 vcc, s0, v214
	v_add_u32_e32 v214, 35, v0
	s_nop 0
	v_cndmask_b32_e32 v82, v210, v82, vcc
	v_cmp_lt_u32_e32 vcc, s0, v214
	v_add_u32_e32 v214, 40, v0
	s_nop 0
	v_cndmask_b32_e32 v83, v210, v83, vcc
	v_cmp_lt_u32_e32 vcc, s0, v214
	v_add_u32_e32 v214, 41, v0
	s_nop 0
	v_cndmask_b32_e32 v84, v210, v84, vcc
	v_cmp_lt_u32_e32 vcc, s0, v214
	v_add_u32_e32 v214, 42, v0
	s_nop 0
	v_cndmask_b32_e32 v85, v210, v85, vcc
	v_cmp_lt_u32_e32 vcc, s0, v214
	v_add_u32_e32 v214, 43, v0
	s_nop 0
	v_cndmask_b32_e32 v86, v210, v86, vcc
	v_cmp_lt_u32_e32 vcc, s0, v214
	v_add_u32_e32 v214, 48, v0
	s_nop 0
	v_cndmask_b32_e32 v87, v210, v87, vcc
	v_cmp_lt_u32_e32 vcc, s0, v214
	v_add_u32_e32 v214, 49, v0
	s_nop 0
	v_cndmask_b32_e32 v88, v210, v88, vcc
	v_cmp_lt_u32_e32 vcc, s0, v214
	v_add_u32_e32 v214, 50, v0
	s_nop 0
	v_cndmask_b32_e32 v89, v210, v89, vcc
	v_cmp_lt_u32_e32 vcc, s0, v214
	v_add_u32_e32 v214, 51, v0
	s_nop 0
	v_cndmask_b32_e32 v90, v210, v90, vcc
	v_cmp_lt_u32_e32 vcc, s0, v214
	v_add_u32_e32 v214, 56, v0
	s_nop 0
	v_cndmask_b32_e32 v91, v210, v91, vcc
	v_cmp_lt_u32_e32 vcc, s0, v214
	v_add_u32_e32 v214, 57, v0
	s_nop 0
	v_cndmask_b32_e32 v92, v210, v92, vcc
	v_cmp_lt_u32_e32 vcc, s0, v214
	v_add_u32_e32 v214, 58, v0
	v_add_u32_e32 v0, 59, v0
	v_cndmask_b32_e32 v93, v210, v93, vcc
	v_cmp_lt_u32_e32 vcc, s0, v214
	s_nop 1
	v_cndmask_b32_e32 v94, v210, v94, vcc
	v_cmp_lt_u32_e32 vcc, s0, v0
	s_nop 1
	v_cndmask_b32_e32 v95, v210, v95, vcc

.LBB0_131:
	s_or_b64 exec, exec, s[44:45]
	s_and_b64 vcc, exec, s[28:29]
	s_waitcnt lgkmcnt(0)
	s_barrier
	s_cbranch_vccnz .Lattn_exit
	s_mov_b32 s49, s25
	s_mov_b32 s100, s101
	s_add_i32 s101, s101, 0x4800
	s_cmp_eq_u32 s101, 0xd800
	s_cselect_b32 s101, 0, s101
	s_branch .LBB0_115
.Lattn_exit:
	v_readlane_b32 s98, v254, 54
	s_nop 3
	s_cmp_ge_u32 s98, 4
	s_cbranch_scc1 .LBB0_91
	s_barrier
	s_branch .LBB0_91
.Lattn_skipx:
	s_waitcnt lgkmcnt(0)
	s_barrier
	s_branch .LBB0_131
